# SCHED re-packed a third time (h5/h6 item costs raised)
# baseline (speedup 1.0000x reference)
_ZL5SCHED:
	.short	424
	.short	65535
	.short	65535
	.short	422
	.short	65535
	.short	65535
	.short	487
	.short	65535
	.short	65535
	.short	360
	.short	65535
	.short	65535
	.short	488
	.short	65535
	.short	65535
	.short	423
	.short	65535
	.short	65535
	.short	359
	.short	65535
	.short	65535
	.short	486
	.short	128
	.short	65535
	.short	485
	.short	0
	.short	65535
	.short	421
	.short	192
	.short	65535
	.short	358
	.short	448
	.short	65535
	.short	420
	.short	449
	.short	65535
	.short	482
	.short	56
	.short	65535
	.short	417
	.short	195
	.short	65535
	.short	357
	.short	64
	.short	65535
	.short	355
	.short	193
	.short	65535
	.short	353
	.short	44
	.short	65535
	.short	354
	.short	386
	.short	65535
	.short	484
	.short	257
	.short	65535
	.short	418
	.short	34
	.short	65535
	.short	419
	.short	321
	.short	65535
	.short	483
	.short	66
	.short	65535
	.short	352
	.short	67
	.short	65535
	.short	480
	.short	114
	.short	65535
	.short	83
	.short	1407
	.short	65535
	.short	389
	.short	1534
	.short	65535
	.short	350
	.short	123
	.short	65535
	.short	79
	.short	1470
	.short	65535
	.short	71
	.short	1535
	.short	65535
	.short	289
	.short	157
	.short	65535
	.short	302
	.short	184
	.short	65535
	.short	412
	.short	456
	.short	65535
	.short	301
	.short	174
	.short	65535
	.short	1022
	.short	158
	.short	65535
	.short	479
	.short	261
	.short	65535
	.short	134
	.short	1533
	.short	65535
	.short	287
	.short	191
	.short	65535
	.short	416
	.short	78
	.short	65535
	.short	313
	.short	155
	.short	65535
	.short	308
	.short	136
	.short	65535
	.short	349
	.short	325
	.short	65535
	.short	327
	.short	1529
	.short	65535
	.short	285
	.short	169
	.short	65535
	.short	188
	.short	1403
	.short	65535
	.short	887
	.short	266
	.short	65535
	.short	294
	.short	263
	.short	65535
	.short	1023
	.short	162
	.short	65535
	.short	307
	.short	199
	.short	65535
	.short	284
	.short	151
	.short	65535
	.short	356
	.short	320
	.short	65535
	.short	319
	.short	178
	.short	65535
	.short	315
	.short	175
	.short	65535
	.short	314
	.short	164
	.short	65535
	.short	299
	.short	166
	.short	65535
	.short	348
	.short	160
	.short	65535
	.short	414
	.short	198
	.short	65535
	.short	1021
	.short	140
	.short	65535
	.short	958
	.short	163
	.short	65535
	.short	956
	.short	149
	.short	65535
	.short	144
	.short	1467
	.short	65535
	.short	138
	.short	1530
	.short	65535
	.short	477
	.short	159
	.short	65535
	.short	76
	.short	1471
	.short	65535
	.short	481
	.short	452
	.short	65535
	.short	296
	.short	391
	.short	65535
	.short	318
	.short	154
	.short	65535
	.short	306
	.short	156
	.short	65535
	.short	351
	.short	388
	.short	65535
	.short	291
	.short	148
	.short	65535
	.short	454
	.short	1406
	.short	65535
	.short	303
	.short	171
	.short	65535
	.short	304
	.short	142
	.short	65535
	.short	202
	.short	1398
	.short	65535
	.short	173
	.short	1404
	.short	65535
	.short	293
	.short	167
	.short	65535
	.short	288
	.short	186
	.short	65535
	.short	415
	.short	103
	.short	65535
	.short	316
	.short	145
	.short	65535
	.short	390
	.short	1405
	.short	65535
	.short	292
	.short	189
	.short	65535
	.short	957
	.short	190
	.short	65535
	.short	954
	.short	328
	.short	65535
	.short	152
	.short	1466
	.short	65535
	.short	120
	.short	1
	.short	1527
	.short	410
	.short	106
	.short	50
	.short	890
	.short	21
	.short	53
	.short	1018
	.short	108
	.short	385
	.short	891
	.short	88
	.short	129
	.short	282
	.short	110
	.short	16
	.short	892
	.short	99
	.short	450
	.short	37
	.short	28
	.short	1464
	.short	889
	.short	11
	.short	36
	.short	346
	.short	38
	.short	29
	.short	952
	.short	324
	.short	55
	.short	326
	.short	1468
	.short	65535
	.short	300
	.short	176
	.short	65535
	.short	959
	.short	135
	.short	65535
	.short	262
	.short	1469
	.short	65535
	.short	311
	.short	170
	.short	65535
	.short	413
	.short	143
	.short	65535
	.short	478
	.short	455
	.short	65535
	.short	1020
	.short	200
	.short	65535
	.short	312
	.short	180
	.short	65535
	.short	888
	.short	265
	.short	65535
	.short	309
	.short	185
	.short	65535
	.short	317
	.short	181
	.short	65535
	.short	286
	.short	146
	.short	65535
	.short	295
	.short	179
	.short	65535
	.short	165
	.short	1532
	.short	65535
	.short	347
	.short	147
	.short	65535
	.short	290
	.short	183
	.short	65535
	.short	264
	.short	1401
	.short	65535
	.short	297
	.short	168
	.short	65535
	.short	187
	.short	1531
	.short	65535
	.short	298
	.short	150
	.short	65535
	.short	305
	.short	139
	.short	65535
	.short	141
	.short	1465
	.short	65535
	.short	457
	.short	1463
	.short	65535
	.short	953
	.short	329
	.short	65535
	.short	310
	.short	182
	.short	65535
	.short	476
	.short	392
	.short	65535
	.short	172
	.short	1402
	.short	65535
	.short	458
	.short	1462
	.short	65535
	.short	283
	.short	201
	.short	65535
	.short	45
	.short	26
	.short	1400
	.short	1016
	.short	90
	.short	5
	.short	895
	.short	72
	.short	20
	.short	345
	.short	98
	.short	194
	.short	474
	.short	74
	.short	47
	.short	127
	.short	51
	.short	1395
	.short	408
	.short	73
	.short	260
	.short	82
	.short	104
	.short	1520
	.short	281
	.short	69
	.short	57
	.short	137
	.short	10
	.short	1455
	.short	886
	.short	118
	.short	48
	.short	115
	.short	65
	.short	1399
	.short	33
	.short	3
	.short	1528
	.short	1017
	.short	89
	.short	258
	.short	95
	.short	4
	.short	1525
	.short	955
	.short	41
	.short	58
	.short	409
	.short	100
	.short	25
	.short	951
	.short	117
	.short	49
	.short	111
	.short	6
	.short	1459
	.short	894
	.short	80
	.short	14
	.short	885
	.short	116
	.short	40
	.short	883
	.short	113
	.short	259
	.short	339
	.short	153
	.short	85
	.short	882
	.short	101
	.short	196
	.short	475
	.short	323
	.short	62
	.short	949
	.short	133
	.short	8
	.short	93
	.short	132
	.short	1393
	.short	950
	.short	102
	.short	12
	.short	94
	.short	22
	.short	1524
	.short	92
	.short	46
	.short	1523
	.short	1011
	.short	121
	.short	87
	.short	1014
	.short	119
	.short	9
	.short	473
	.short	453
	.short	32
	.short	75
	.short	2
	.short	1461
	.short	96
	.short	130
	.short	1526
	.short	881
	.short	70
	.short	86
	.short	105
	.short	387
	.short	1394
	.short	884
	.short	124
	.short	35
	.short	112
	.short	27
	.short	1396
	.short	1015
	.short	122
	.short	42
	.short	280
	.short	107
	.short	68
	.short	1019
	.short	59
	.short	54
	.short	342
	.short	97
	.short	126
	.short	197
	.short	18
	.short	1458
	.short	109
	.short	30
	.short	1460
	.short	279
	.short	177
	.short	17
	.short	81
	.short	125
	.short	1392
	.short	893
	.short	91
	.short	19
	.short	344
	.short	84
	.short	52
	.short	946
	.short	161
	.short	24
	.short	1004
	.short	330
	.short	31
	.short	77
	.short	39
	.short	1397
	.short	276
	.short	394
	.short	7
	.short	411
	.short	393
	.short	65535
	.short	948
	.short	396
	.short	65535
	.short	460
	.short	1522
	.short	65535
	.short	343
	.short	204
	.short	65535
	.short	472
	.short	269
	.short	65535
	.short	268
	.short	1457
	.short	65535
	.short	275
	.short	274
	.short	65535
	.short	877
	.short	246
	.short	65535
	.short	333
	.short	1519
	.short	65535
	.short	237
	.short	1450
	.short	65535
	.short	407
	.short	462
	.short	65535
	.short	461
	.short	1521
	.short	65535
	.short	215
	.short	1518
	.short	65535
	.short	224
	.short	1454
	.short	65535
	.short	879
	.short	248
	.short	65535
	.short	874
	.short	465
	.short	65535
	.short	334
	.short	1514
	.short	65535
	.short	220
	.short	1452
	.short	65535
	.short	947
	.short	397
	.short	65535
	.short	340
	.short	247
	.short	65535
	.short	255
	.short	1451
	.short	65535
	.short	1010
	.short	398
	.short	65535
	.short	944
	.short	211
	.short	65535
	.short	205
	.short	1456
	.short	65535
	.short	943
	.short	225
	.short	65535
	.short	1005
	.short	399
	.short	65535
	.short	1008
	.short	242
	.short	65535
	.short	471
	.short	252
	.short	65535
	.short	1009
	.short	244
	.short	65535
	.short	270
	.short	1391
	.short	65535
	.short	945
	.short	245
	.short	65535
	.short	876
	.short	233
	.short	65535
	.short	1006
	.short	222
	.short	65535
	.short	213
	.short	1389
	.short	65535
	.short	1003
	.short	336
	.short	65535
	.short	250
	.short	1390
	.short	65535
	.short	464
	.short	1449
	.short	65535
	.short	212
	.short	1387
	.short	65535
	.short	467
	.short	402
	.short	65535
	.short	278
	.short	240
	.short	65535
	.short	469
	.short	217
	.short	65535
	.short	878
	.short	230
	.short	65535
	.short	1007
	.short	239
	.short	65535
	.short	463
	.short	1386
	.short	65535
	.short	1012
	.short	332
	.short	65535
	.short	1013
	.short	331
	.short	65535
	.short	875
	.short	271
	.short	65535
	.short	338
	.short	401
	.short	65535
	.short	940
	.short	335
	.short	65535
	.short	277
	.short	229
	.short	65535
	.short	873
	.short	273
	.short	65535
	.short	406
	.short	253
	.short	65535
	.short	880
	.short	206
	.short	65535
	.short	404
	.short	400
	.short	65535
	.short	234
	.short	1515
	.short	65535
	.short	942
	.short	208
	.short	65535
	.short	938
	.short	466
	.short	65535
	.short	272
	.short	1385
	.short	65535
	.short	243
	.short	1388
	.short	65535
	.short	470
	.short	218
	.short	65535
	.short	238
	.short	1453
	.short	65535
	.short	227
	.short	1517
	.short	65535
	.short	941
	.short	249
	.short	65535
	.short	221
	.short	1516
	.short	65535
	.short	341
	.short	251
	.short	65535
	.short	223
	.short	235
	.short	13
	.short	937
	.short	210
	.short	256
	.short	228
	.short	207
	.short	451
	.short	1001
	.short	216
	.short	384
	.short	459
	.short	43
	.short	1513
	.short	468
	.short	203
	.short	15
	.short	214
	.short	254
	.short	322
	.short	939
	.short	267
	.short	63
	.short	219
	.short	232
	.short	61
	.short	1002
	.short	337
	.short	65535
	.short	226
	.short	241
	.short	131
	.short	236
	.short	209
	.short	60
	.short	403
	.short	395
	.short	23
	.short	405
	.short	231
	.short	65535
	.size	_ZL5SCHED, 1536

	.type	__hip_cuid_3f0aab64d1338eba,@object
